# sel_ipc: hand-written in-place unmasked selected-pair body; row part of the position bias folded into the QK accumulator init (one bias add per 4 scores)
# baseline (speedup 1.0000x reference)
.LBB0_1038:
	s_or_b64 exec, exec, s[0:1]
	s_bcnt1_i32_b32 s0, s21
	s_bcnt1_i32_b32 s1, s22
	s_bcnt1_i32_b32 s21, s23
	s_lshl_b32 s22, s40, 25
	s_add_u32 s22, s36, s22
	s_addc_u32 s23, s37, 0
	s_bcnt1_i32_b32 s20, s20
	s_add_i32 s0, s0, s20
	s_add_i32 s79, s0, s1
	s_add_i32 s79, s79, s21
	s_lshl_b32 s0, s29, 7
	s_add_u32 s24, s22, s0
	v_sub_co_u32_e64 v32, s[0:1], s79, 1
	s_waitcnt lgkmcnt(0)
	s_barrier
	s_addc_u32 s25, s23, 0
	s_lshl_b32 s0, s47, 20
	s_add_u32 s20, s55, s0
	s_addc_u32 s21, s56, 0
	v_add_u32_e32 v8, -2, v32
	v_max_i32_e32 v8, 0, v8
	v_add_u32_e32 v9, -3, v32
	v_max_i32_e32 v9, 0, v9
	v_lshl_add_u32 v8, v8, 2, s72
	v_lshl_add_u32 v9, v9, 2, s72
	ds_read_b32 v8, v8
	ds_read_b32 v9, v9
	s_ashr_i32 s32, s75, 2
	s_add_i32 s97, s32, -1
	s_max_i32 s97, s97, 0
	s_cmp_lt_u32 s79, 2
	s_cselect_b64 vcc, -1, 0
	v_mov_b32_e32 v139, v123
	v_mov_b32_e32 v141, v123
	v_readfirstlane_b32 s80, v32
	v_add_f32_e32 v137, v146, v146
	v_mul_f32_e32 v188, 0x40400000, v146
	v_mul_f32_e32 v189, 0x41800000, v146
	v_mul_f32_e32 v190, 0x42000000, v146
	v_mul_f32_e32 v191, 0x42400000, v146
	v_mul_f32_e32 v192, 0, v146
	v_mov_b32_e32 v234, 0
	v_mul_f32_e32 v235, 0x40b17218, v146
	v_add_f32_e32 v238, v235, v235
	v_mul_f32_e32 v239, 0x40400000, v235
	s_waitcnt vmcnt(0)
	ds_write_b128 v151, v[240:243]
	ds_write2_b64 v187, v[244:245], v[246:247] offset1:2
	ds_write_b128 v151, v[248:251] offset:10240
	ds_write2_b64 v186, v[252:253], v[254:255] offset1:2
	s_lshl_b32 s98, s47, 20
	s_add_u32 s98, s57, s98
	s_addc_u32 s99, s60, 0
	s_add_i32 s29, s74, 0xfffffe01
	s_andn2_b32 s29, s29, 63
	s_cmp_gt_i32 s75, 31
	s_cselect_b32 s29, s29, 0
	s_sub_i32 s30, s74, s29
	s_ashr_i32 s30, s30, 6
	v_mov_b32_e32 v4, v138
	v_mov_b32_e32 v5, 0
	v_mov_b32_e32 v6, v140
	v_mov_b32_e32 v7, 0
	s_min_i32 s22, s30, 0
	s_lshl_b32 s22, s22, 6
	s_add_i32 s22, s22, s29
	s_ashr_i32 s23, s22, 31
	s_lshl_b64 s[100:101], s[22:23], 12
	s_add_u32 s100, s24, s100
	s_addc_u32 s101, s25, s101
	s_lshl_b64 s[22:23], s[22:23], 1
	s_add_u32 s22, s98, s22
	s_addc_u32 s23, s99, s23
	v_lshl_add_u64 v[0:1], s[100:101], 0, v[4:5]
	v_lshl_add_u64 v[2:3], s[22:23], 0, v[6:7]
	v_lshl_add_u64 v[0:1], v[0:1], 0, v[122:123]
	v_lshl_add_u64 v[2:3], v[2:3], 0, v[122:123]
	global_load_dwordx4 v[240:243], v[0:1], off offset:3072
	global_load_dwordx4 v[244:247], v[2:3], off
	s_min_i32 s22, s30, 1
	s_lshl_b32 s22, s22, 6
	s_add_i32 s22, s22, s29
	s_ashr_i32 s23, s22, 31
	s_lshl_b64 s[100:101], s[22:23], 12
	s_add_u32 s100, s24, s100
	s_addc_u32 s101, s25, s101
	s_lshl_b64 s[22:23], s[22:23], 1
	s_add_u32 s22, s98, s22
	s_addc_u32 s23, s99, s23
	v_lshl_add_u64 v[0:1], s[100:101], 0, v[4:5]
	v_lshl_add_u64 v[2:3], s[22:23], 0, v[6:7]
	v_lshl_add_u64 v[0:1], v[0:1], 0, v[122:123]
	v_lshl_add_u64 v[2:3], v[2:3], 0, v[122:123]
	global_load_dwordx4 v[248:251], v[0:1], off offset:3072
	global_load_dwordx4 v[252:255], v[2:3], off
	s_waitcnt lgkmcnt(4)
	v_readfirstlane_b32 s89, v8
	v_readfirstlane_b32 s91, v9
	s_lshl_b32 s0, s89, 6
	s_ashr_i32 s1, s0, 31
	s_lshl_b64 s[22:23], s[0:1], 12
	s_add_u32 s22, s24, s22
	s_addc_u32 s23, s25, s23
	s_lshl_b64 s[0:1], s[0:1], 1
	s_add_u32 s0, s20, s0
	s_addc_u32 s1, s21, s1
	v_lshl_add_u64 v[0:1], s[22:23], 0, v[138:139]
	v_lshl_add_u64 v[2:3], s[0:1], 0, v[140:141]
	v_lshl_add_u64 v[0:1], v[0:1], 0, v[122:123]
	v_lshl_add_u64 v[2:3], v[2:3], 0, v[122:123]
	global_load_dwordx4 v[20:23], v[0:1], off offset:2560
	global_load_dwordx4 v[16:19], v[2:3], off
	s_lshl_b32 s0, s91, 6
	s_ashr_i32 s1, s0, 31
	s_lshl_b64 s[22:23], s[0:1], 12
	s_add_u32 s22, s24, s22
	s_addc_u32 s23, s25, s23
	s_lshl_b64 s[0:1], s[0:1], 1
	s_add_u32 s0, s20, s0
	s_addc_u32 s1, s21, s1
	v_lshl_add_u64 v[4:5], s[22:23], 0, v[138:139]
	v_lshl_add_u64 v[6:7], s[0:1], 0, v[140:141]
	v_lshl_add_u64 v[4:5], v[4:5], 0, v[122:123]
	v_lshl_add_u64 v[6:7], v[6:7], 0, v[122:123]
	global_load_dwordx4 v[28:31], v[4:5], off offset:2560
	global_load_dwordx4 v[24:27], v[6:7], off
	s_waitcnt lgkmcnt(0)
	s_barrier
	v_lshl_add_u64 v[0:1], s[24:25], 0, v[138:139]
	v_lshl_add_u64 v[120:121], v[0:1], 0, v[122:123]
	s_and_b64 vcc, exec, vcc
	s_cbranch_vccnz .LBB0_1050
	v_lshl_add_u64 v[0:1], s[20:21], 0, v[140:141]
	v_mov_b32_e32 v36, 0
	v_lshl_add_u64 v[148:149], v[0:1], 0, v[122:123]
	v_sub_u32_e32 v139, v144, v124
	v_mov_b32_e32 v32, v123
	v_mov_b32_e32 v33, v123
	v_mov_b32_e32 v34, v123
	v_mov_b32_e32 v35, v123
	s_mov_b32 s83, 5
	s_movk_i32 s81, 0x80
	s_mov_b32 s82, s72
	v_mov_b32_e32 v37, v36
	v_mov_b32_e32 v38, v36
	v_mov_b32_e32 v39, v36
	v_mov_b32_e32 v40, v36
	v_mov_b32_e32 v41, v36
	v_mov_b32_e32 v42, v36
	v_mov_b32_e32 v43, v36
	v_mov_b32_e32 v44, v36
	v_mov_b32_e32 v45, v36
	v_mov_b32_e32 v46, v36
	v_mov_b32_e32 v47, v36
	v_mov_b32_e32 v84, v36
	v_mov_b32_e32 v85, v36
	v_mov_b32_e32 v86, v36
	v_mov_b32_e32 v87, v36

.LBB0_1046:
	s_andn2_b64 vcc, exec, s[22:23]
	s_cbranch_vccnz .LBB0_1048
	s_mov_b32 s101, 0
	s_mov_b32 s29, s28
	v_pk_mov_b32 v[226:227], v[234:235], v[234:235] op_sel:[0,1]
	v_pk_mov_b32 v[228:229], v[238:239], v[238:239] op_sel:[0,1]
	s_sub_i32 s22, s81, 64
	s_and_b32 s22, s22, 0xc0
	s_mulk_i32 s22, 0xa0
	v_add_u32_e32 v193, s22, v153
	v_pk_mov_b32 v[80:81], s[28:29], s[28:29] op_sel:[0,1]
	v_pk_mov_b32 v[82:83], s[28:29], s[28:29] op_sel:[0,1]
	s_waitcnt lgkmcnt(7)
	v_mfma_f32_16x16x32_bf16 v[0:3], v[88:91], v[60:63], v[226:229]
	s_waitcnt lgkmcnt(5)
	v_mfma_f32_16x16x32_bf16 v[4:7], v[96:99], v[60:63], v[226:229]
	s_waitcnt lgkmcnt(3)
	v_mfma_f32_16x16x32_bf16 v[8:11], v[104:107], v[60:63], v[226:229]
	s_waitcnt lgkmcnt(1)
	v_mfma_f32_16x16x32_bf16 v[12:15], v[112:115], v[60:63], v[226:229]
	v_mfma_f32_16x16x32_bf16 v[0:3], v[92:95], v[56:59], v[0:3]
	v_mfma_f32_16x16x32_bf16 v[4:7], v[100:103], v[56:59], v[4:7]
	v_mfma_f32_16x16x32_bf16 v[8:11], v[108:111], v[56:59], v[8:11]
	s_waitcnt lgkmcnt(0)
	v_mfma_f32_16x16x32_bf16 v[12:15], v[116:119], v[56:59], v[12:15]
	s_setprio 0
	ds_read_b128 v[88:91], v143 offset:40960
	ds_read_b128 v[92:95], v143 offset:43520
	ds_read_b128 v[96:99], v143 offset:46080
	ds_read_b128 v[100:103], v143 offset:48640
	ds_read_b128 v[104:107], v143 offset:41024
	ds_read_b128 v[108:111], v143 offset:43584
	ds_read_b128 v[112:115], v143 offset:46144
	ds_read_b128 v[116:119], v143 offset:48704
	ds_read_b128 v[194:197], v193
	ds_read_b128 v[198:201], v193 offset:64
	ds_read_b128 v[202:205], v193 offset:2560
	ds_read_b128 v[206:209], v193 offset:2624
	ds_read_b128 v[210:213], v193 offset:5120
	ds_read_b128 v[214:217], v193 offset:5184
	ds_read_b128 v[218:221], v193 offset:7680
	v_mul_f32_e64 v230, -v146, v147
	v_cndmask_b32_e64 v230, v179, v230, s[20:21]
	v_add_f32_e32 v231, v192, v230
	v_fmamk_f32 v0, v0, 0x3e38aa3b, v231
	v_fmamk_f32 v1, v1, 0x3e38aa3b, v231
	v_fmamk_f32 v2, v2, 0x3e38aa3b, v231
	v_fmamk_f32 v3, v3, 0x3e38aa3b, v231
	v_exp_f32_e32 v0, v0
	v_exp_f32_e32 v1, v1
	v_exp_f32_e32 v2, v2
	v_exp_f32_e32 v3, v3
	v_add_f32_e32 v231, v189, v230
	v_fmamk_f32 v4, v4, 0x3e38aa3b, v231
	v_fmamk_f32 v5, v5, 0x3e38aa3b, v231
	v_fmamk_f32 v6, v6, 0x3e38aa3b, v231
	v_fmamk_f32 v7, v7, 0x3e38aa3b, v231
	v_exp_f32_e32 v4, v4
	v_exp_f32_e32 v5, v5
	v_exp_f32_e32 v6, v6
	v_exp_f32_e32 v7, v7
	v_add_f32_e32 v231, v190, v230
	v_fmamk_f32 v8, v8, 0x3e38aa3b, v231
	v_fmamk_f32 v9, v9, 0x3e38aa3b, v231
	v_fmamk_f32 v10, v10, 0x3e38aa3b, v231
	v_fmamk_f32 v11, v11, 0x3e38aa3b, v231
	v_exp_f32_e32 v8, v8
	v_exp_f32_e32 v9, v9
	v_exp_f32_e32 v10, v10
	v_exp_f32_e32 v11, v11
	v_add_f32_e32 v231, v191, v230
	v_fmamk_f32 v12, v12, 0x3e38aa3b, v231
	v_fmamk_f32 v13, v13, 0x3e38aa3b, v231
	v_fmamk_f32 v14, v14, 0x3e38aa3b, v231
	v_fmamk_f32 v15, v15, 0x3e38aa3b, v231
	v_exp_f32_e32 v12, v12
	v_exp_f32_e32 v13, v13
	v_exp_f32_e32 v14, v14
	v_exp_f32_e32 v15, v15
	v_cvt_pk_bf16_f32 v226, v0, v1
	v_cvt_pk_bf16_f32 v227, v2, v3
	v_cvt_pk_bf16_f32 v228, v4, v5
	v_cvt_pk_bf16_f32 v229, v6, v7
	v_cvt_pk_bf16_f32 v230, v8, v9
	v_cvt_pk_bf16_f32 v231, v10, v11
	v_cvt_pk_bf16_f32 v232, v12, v13
	v_cvt_pk_bf16_f32 v233, v14, v15
	s_nop 1
	s_setprio 1
	s_waitcnt lgkmcnt(14)
	v_mfma_f32_16x16x32_bf16 v[36:39], v[88:91], v[226:229], v[36:39]
	ds_read_b128 v[222:225], v193 offset:7744
	s_waitcnt lgkmcnt(14)
	v_mfma_f32_16x16x32_bf16 v[40:43], v[92:95], v[226:229], v[40:43]
	s_waitcnt lgkmcnt(13)
	v_mfma_f32_16x16x32_bf16 v[44:47], v[96:99], v[226:229], v[44:47]
	s_waitcnt lgkmcnt(12)
	v_mfma_f32_16x16x32_bf16 v[84:87], v[100:103], v[226:229], v[84:87]
	v_mfma_f32_16x16x32_bf16 v[32:35], v[80:83], v[226:229], v[32:35]
	s_waitcnt lgkmcnt(11)
	v_mfma_f32_16x16x32_bf16 v[36:39], v[104:107], v[230:233], v[36:39]
	s_waitcnt lgkmcnt(10)
	v_mfma_f32_16x16x32_bf16 v[40:43], v[108:111], v[230:233], v[40:43]
	s_waitcnt lgkmcnt(9)
	v_mfma_f32_16x16x32_bf16 v[44:47], v[112:115], v[230:233], v[44:47]
	s_waitcnt lgkmcnt(8)
	v_mfma_f32_16x16x32_bf16 v[84:87], v[116:119], v[230:233], v[84:87]
	v_mfma_f32_16x16x32_bf16 v[32:35], v[80:83], v[230:233], v[32:35]
	v_pk_mov_b32 v[226:227], v[234:235], v[234:235] op_sel:[0,1]
	v_pk_mov_b32 v[228:229], v[238:239], v[238:239] op_sel:[0,1]
	s_nop 1
	s_waitcnt lgkmcnt(7)
	v_mfma_f32_16x16x32_bf16 v[0:3], v[194:197], v[60:63], v[226:229]
	s_waitcnt lgkmcnt(5)
	v_mfma_f32_16x16x32_bf16 v[4:7], v[202:205], v[60:63], v[226:229]
	s_waitcnt lgkmcnt(3)
	v_mfma_f32_16x16x32_bf16 v[8:11], v[210:213], v[60:63], v[226:229]
	s_waitcnt lgkmcnt(1)
	v_mfma_f32_16x16x32_bf16 v[12:15], v[218:221], v[60:63], v[226:229]
	v_mfma_f32_16x16x32_bf16 v[0:3], v[198:201], v[56:59], v[0:3]
	v_mfma_f32_16x16x32_bf16 v[4:7], v[206:209], v[56:59], v[4:7]
	v_mfma_f32_16x16x32_bf16 v[8:11], v[214:217], v[56:59], v[8:11]
	s_waitcnt lgkmcnt(0)
	v_mfma_f32_16x16x32_bf16 v[12:15], v[222:225], v[56:59], v[12:15]
	s_setprio 0
	ds_read_b128 v[194:197], v193 offset:40960
	ds_read_b128 v[198:201], v193 offset:43520
	ds_read_b128 v[202:205], v193 offset:46080
	ds_read_b128 v[206:209], v193 offset:48640
	ds_read_b128 v[210:213], v193 offset:41024
	ds_read_b128 v[214:217], v193 offset:43584
	ds_read_b128 v[218:221], v193 offset:46144
	ds_read_b128 v[222:225], v193 offset:48704
	v_mul_f32_e64 v230, -v146, v141
	v_cndmask_b32_e64 v230, v179, v230, s[0:1]
	v_add_f32_e32 v231, v192, v230
	v_fmamk_f32 v0, v0, 0x3e38aa3b, v231
	v_fmamk_f32 v1, v1, 0x3e38aa3b, v231
	v_fmamk_f32 v2, v2, 0x3e38aa3b, v231
	v_fmamk_f32 v3, v3, 0x3e38aa3b, v231
	v_exp_f32_e32 v0, v0
	v_exp_f32_e32 v1, v1
	v_exp_f32_e32 v2, v2
	v_exp_f32_e32 v3, v3
	v_add_f32_e32 v231, v189, v230
	v_fmamk_f32 v4, v4, 0x3e38aa3b, v231
	v_fmamk_f32 v5, v5, 0x3e38aa3b, v231
	v_fmamk_f32 v6, v6, 0x3e38aa3b, v231
	v_fmamk_f32 v7, v7, 0x3e38aa3b, v231
	v_exp_f32_e32 v4, v4
	v_exp_f32_e32 v5, v5
	v_exp_f32_e32 v6, v6
	v_exp_f32_e32 v7, v7
	v_add_f32_e32 v231, v190, v230
	v_fmamk_f32 v8, v8, 0x3e38aa3b, v231
	v_fmamk_f32 v9, v9, 0x3e38aa3b, v231
	v_fmamk_f32 v10, v10, 0x3e38aa3b, v231
	v_fmamk_f32 v11, v11, 0x3e38aa3b, v231
	v_exp_f32_e32 v8, v8
	v_exp_f32_e32 v9, v9
	v_exp_f32_e32 v10, v10
	v_exp_f32_e32 v11, v11
	v_add_f32_e32 v231, v191, v230
	v_fmamk_f32 v12, v12, 0x3e38aa3b, v231
	v_fmamk_f32 v13, v13, 0x3e38aa3b, v231
	v_fmamk_f32 v14, v14, 0x3e38aa3b, v231
	v_fmamk_f32 v15, v15, 0x3e38aa3b, v231
	v_exp_f32_e32 v12, v12
	v_exp_f32_e32 v13, v13
	v_exp_f32_e32 v14, v14
	v_exp_f32_e32 v15, v15
	v_cvt_pk_bf16_f32 v226, v0, v1
	v_cvt_pk_bf16_f32 v227, v2, v3
	v_cvt_pk_bf16_f32 v228, v4, v5
	v_cvt_pk_bf16_f32 v229, v6, v7
	v_cvt_pk_bf16_f32 v230, v8, v9
	v_cvt_pk_bf16_f32 v231, v10, v11
	v_cvt_pk_bf16_f32 v232, v12, v13
	v_cvt_pk_bf16_f32 v233, v14, v15
	s_nop 1
	s_setprio 1
	s_waitcnt lgkmcnt(7)
	v_mfma_f32_16x16x32_bf16 v[36:39], v[194:197], v[226:229], v[36:39]
	s_waitcnt lgkmcnt(6)
	v_mfma_f32_16x16x32_bf16 v[40:43], v[198:201], v[226:229], v[40:43]
	s_waitcnt lgkmcnt(5)
	v_mfma_f32_16x16x32_bf16 v[44:47], v[202:205], v[226:229], v[44:47]
	s_waitcnt lgkmcnt(4)
	v_mfma_f32_16x16x32_bf16 v[84:87], v[206:209], v[226:229], v[84:87]
	v_mfma_f32_16x16x32_bf16 v[32:35], v[80:83], v[226:229], v[32:35]
	s_waitcnt lgkmcnt(3)
	v_mfma_f32_16x16x32_bf16 v[36:39], v[210:213], v[230:233], v[36:39]
	s_waitcnt lgkmcnt(2)
	v_mfma_f32_16x16x32_bf16 v[40:43], v[214:217], v[230:233], v[40:43]
	s_waitcnt lgkmcnt(1)
	v_mfma_f32_16x16x32_bf16 v[44:47], v[218:221], v[230:233], v[44:47]
	s_waitcnt lgkmcnt(0)
	v_mfma_f32_16x16x32_bf16 v[84:87], v[222:225], v[230:233], v[84:87]
	v_mfma_f32_16x16x32_bf16 v[32:35], v[80:83], v[230:233], v[32:35]
